# T1: diff loop without score-init copy, scalar-base tile loads (on G1+EP1)
# speedup vs baseline: 1.0425x; 1.0098x over previous
.LBB0_695:
	v_mov_b32_e32 v14, v1
	v_mov_b32_e32 v15, v1
	v_lshl_add_u64 v[138:139], s[0:1], 0, v[0:1]
	v_add_u32_e32 v150, 0x80, v4
	v_add_u32_e32 v151, 0x80, v2
	v_mov_b32_e32 v0, v1
	v_mov_b32_e32 v2, v1
	v_mov_b32_e32 v3, v1
	v_mov_b32_e32 v4, v1
	v_mov_b32_e32 v5, v1
	v_mov_b32_e32 v6, v1
	v_mov_b32_e32 v7, v1
	v_mov_b32_e32 v8, v1
	v_mov_b32_e32 v9, v1
	v_mov_b32_e32 v10, v1
	v_mov_b32_e32 v11, v1
	v_mov_b32_e32 v12, v1
	v_mov_b32_e32 v13, v1
	v_mov_b32_e32 v48, 0x42000000
	v_mov_b64_e32 v[30:31], v[14:15]
	v_mov_b64_e32 v[46:47], v[14:15]
	v_lshlrev_b32_e32 v147, 3, v140
	s_or_b32 s5, s5, 31
	v_mul_u32_u24_e32 v148, 0x90, v141
	v_lshlrev_b32_e32 v125, 2, v140
	v_mul_u32_u24_e32 v149, 0x88, v141
	s_mov_b32 s7, 0
	v_mov_b32_e32 v153, 0xc2000000
	v_mov_b32_e32 v152, 0
	v_mov_b64_e32 v[28:29], v[12:13]
	v_mov_b64_e32 v[26:27], v[10:11]
	v_mov_b64_e32 v[24:25], v[8:9]
	v_mov_b64_e32 v[22:23], v[6:7]
	v_mov_b64_e32 v[20:21], v[4:5]
	v_mov_b64_e32 v[18:19], v[2:3]
	v_mov_b64_e32 v[16:17], v[0:1]
	v_mov_b64_e32 v[44:45], v[12:13]
	v_mov_b64_e32 v[42:43], v[10:11]
	v_mov_b64_e32 v[40:41], v[8:9]
	v_mov_b64_e32 v[38:39], v[6:7]
	v_mov_b64_e32 v[36:37], v[4:5]
	v_mov_b64_e32 v[34:35], v[2:3]
	v_mov_b64_e32 v[32:33], v[0:1]
	s_mov_b32 s0, 0
	s_mov_b32 s8, 0
	v_mov_b32_e32 v49, v48
	v_mov_b32_e32 v50, v48
	v_mov_b32_e32 v51, v48
	v_mov_b32_e32 v52, v48
	v_mov_b32_e32 v53, v48
	v_mov_b32_e32 v54, v48
	v_mov_b32_e32 v55, v48
	v_mov_b32_e32 v56, v48
	v_mov_b32_e32 v57, v48
	v_mov_b32_e32 v58, v48
	v_mov_b32_e32 v59, v48
	v_mov_b32_e32 v60, v48
	v_mov_b32_e32 v61, v48
	v_mov_b32_e32 v62, v48
	v_mov_b32_e32 v63, v48
	s_and_b32 s10, s13, 7
	s_lshl_b32 s10, s10, 20
	v_readlane_b32 s16, v234, 44
	v_readlane_b32 s17, v234, 45
	v_readlane_b32 s11, v234, 42
	v_readlane_b32 s12, v234, 43
	s_add_u32 s16, s16, s10
	s_addc_u32 s17, s17, 0
	s_add_u32 s10, s11, s10
	s_addc_u32 s11, s12, 0
	s_add_u32 s18, s16, 0x4000
	s_addc_u32 s12, s17, 0
	s_add_u32 s16, s10, 0x100
	s_addc_u32 s17, s11, 0
	s_mov_b32 s10, s18
	s_mov_b32 s11, s12
	v_lshlrev_b32_e32 v180, 4, v156
	v_lshrrev_b32_e32 v182, 3, v156
	v_and_b32_e32 v183, 7, v156
	v_add_u32_e32 v181, 0x1000, v180
	v_lshlrev_b32_e32 v182, 14, v182
	v_lshl_add_u32 v182, v183, 4, v182
	v_add_u32_e32 v183, 0x80000, v182

.LBB0_698:
	s_add_i32 s1, s8, 2
	s_cmp_gt_u32 s1, s4
	s_cbranch_scc1 .LBB0_700
	global_load_dwordx4 v[108:111], v180, s[10:11]
	global_load_dwordx4 v[104:107], v182, s[16:17]
	global_load_dwordx4 v[112:115], v181, s[10:11]
	global_load_dwordx4 v[116:119], v183, s[16:17]
	s_add_u32 s10, s10, 0x2000
	s_addc_u32 s11, s11, 0
	s_add_u32 s16, s16, 0x80
	s_addc_u32 s17, s17, 0
.LBB0_700:
	s_cmp_gt_i32 s7, s5
	s_waitcnt lgkmcnt(0)
	s_barrier
	s_cbranch_scc1 .LBB0_707
	s_mul_i32 s14, s0, 0x4a00
	v_add_u32_e32 v0, s14, v148
	v_add3_u32 v0, v0, v130, v132
	ds_read_b128 v[2:5], v0
	s_waitcnt lgkmcnt(0)
	v_mfma_f32_32x32x16_bf16 v[80:95], v[2:5], v[96:99], v[48:63]
	ds_read_b128 v[2:5], v0 offset:4608
	s_add_i32 s0, s7, 63
	v_cmp_le_i32_e32 vcc, s0, v128
	s_cmp_eq_u64 vcc, exec
	s_waitcnt lgkmcnt(0)
	v_mfma_f32_32x32x16_bf16 v[64:79], v[2:5], v[96:99], v[48:63]
	ds_read_b128 v[2:5], v0 offset:32
	s_waitcnt lgkmcnt(0)
	v_mfma_f32_32x32x16_bf16 v[80:95], v[2:5], v[100:103], v[80:95]
	ds_read_b128 v[2:5], v0 offset:4640
	s_waitcnt lgkmcnt(0)
	v_mfma_f32_32x32x16_bf16 v[64:79], v[2:5], v[100:103], v[64:79]
	s_cbranch_scc1 .LBB0_705
	v_add_u32_e32 v0, s7, v125
	v_cmp_lt_i32_e32 vcc, v0, v128
	v_add_u32_e32 v2, 2, v0
	s_nop 4
	v_cndmask_b32_e32 v81, v169, v81, vcc
	v_cmp_le_i32_e32 vcc, v0, v128
	s_nop 1
	v_cndmask_b32_e32 v80, v169, v80, vcc
	v_cmp_le_i32_e32 vcc, v2, v128
	v_add_u32_e32 v2, 3, v0
	s_nop 0
	v_cndmask_b32_e32 v82, v169, v82, vcc
	v_cmp_le_i32_e32 vcc, v2, v128
	v_add_u32_e32 v2, 8, v0
	s_nop 0
	v_cndmask_b32_e32 v83, v169, v83, vcc
	v_cmp_le_i32_e32 vcc, v2, v128
	v_add_u32_e32 v2, 9, v0
	s_nop 0
	v_cndmask_b32_e32 v84, v169, v84, vcc
	v_cmp_le_i32_e32 vcc, v2, v128
	v_add_u32_e32 v2, 10, v0
	s_nop 0
	v_cndmask_b32_e32 v85, v169, v85, vcc
	v_cmp_le_i32_e32 vcc, v2, v128
	v_add_u32_e32 v2, 11, v0
	s_nop 0
	v_cndmask_b32_e32 v86, v169, v86, vcc
	v_cmp_le_i32_e32 vcc, v2, v128
	v_add_u32_e32 v2, 16, v0
	s_nop 0
	v_cndmask_b32_e32 v87, v169, v87, vcc
	v_cmp_le_i32_e32 vcc, v2, v128
	v_add_u32_e32 v2, 17, v0
	s_nop 0
	v_cndmask_b32_e32 v88, v169, v88, vcc
	v_cmp_le_i32_e32 vcc, v2, v128
	v_add_u32_e32 v2, 18, v0
	s_nop 0
	v_cndmask_b32_e32 v89, v169, v89, vcc
	v_cmp_le_i32_e32 vcc, v2, v128
	v_add_u32_e32 v2, 19, v0
	s_nop 0
	v_cndmask_b32_e32 v90, v169, v90, vcc
	v_cmp_le_i32_e32 vcc, v2, v128
	v_add_u32_e32 v2, 24, v0
	s_nop 0
	v_cndmask_b32_e32 v91, v169, v91, vcc
	v_cmp_le_i32_e32 vcc, v2, v128
	v_add_u32_e32 v2, 25, v0
	s_nop 0
	v_cndmask_b32_e32 v92, v169, v92, vcc
	v_cmp_le_i32_e32 vcc, v2, v128
	v_add_u32_e32 v2, 26, v0
	s_nop 0
	v_cndmask_b32_e32 v93, v169, v93, vcc
	v_cmp_le_i32_e32 vcc, v2, v128
	v_add_u32_e32 v2, 27, v0
	s_nop 0
	v_cndmask_b32_e32 v94, v169, v94, vcc
	v_cmp_le_i32_e32 vcc, v2, v128
	v_add_u32_e32 v2, 32, v0
	s_nop 0
	v_cndmask_b32_e32 v95, v169, v95, vcc
	v_cmp_le_i32_e32 vcc, v2, v128
	v_add_u32_e32 v2, 33, v0
	s_nop 0
	v_cndmask_b32_e32 v64, v169, v64, vcc
	v_cmp_le_i32_e32 vcc, v2, v128
	v_add_u32_e32 v2, 34, v0
	s_nop 0
	v_cndmask_b32_e32 v65, v169, v65, vcc
	v_cmp_le_i32_e32 vcc, v2, v128
	v_add_u32_e32 v2, 35, v0
	s_nop 0
	v_cndmask_b32_e32 v66, v169, v66, vcc
	v_cmp_le_i32_e32 vcc, v2, v128
	v_add_u32_e32 v2, 40, v0
	s_nop 0
	v_cndmask_b32_e32 v67, v169, v67, vcc
	v_cmp_le_i32_e32 vcc, v2, v128
	v_add_u32_e32 v2, 41, v0
	s_nop 0
	v_cndmask_b32_e32 v68, v169, v68, vcc
	v_cmp_le_i32_e32 vcc, v2, v128
	v_add_u32_e32 v2, 42, v0
	s_nop 0
	v_cndmask_b32_e32 v69, v169, v69, vcc
	v_cmp_le_i32_e32 vcc, v2, v128
	v_add_u32_e32 v2, 43, v0
	s_nop 0
	v_cndmask_b32_e32 v70, v169, v70, vcc
	v_cmp_le_i32_e32 vcc, v2, v128
	v_add_u32_e32 v2, 48, v0
	s_nop 0
	v_cndmask_b32_e32 v71, v169, v71, vcc
	v_cmp_le_i32_e32 vcc, v2, v128
	v_add_u32_e32 v2, 49, v0
	s_nop 0
	v_cndmask_b32_e32 v72, v169, v72, vcc
	v_cmp_le_i32_e32 vcc, v2, v128
	v_add_u32_e32 v2, 50, v0
	s_nop 0
	v_cndmask_b32_e32 v73, v169, v73, vcc
	v_cmp_le_i32_e32 vcc, v2, v128
	v_add_u32_e32 v2, 51, v0
	s_nop 0
	v_cndmask_b32_e32 v74, v169, v74, vcc
	v_cmp_le_i32_e32 vcc, v2, v128
	v_add_u32_e32 v2, 56, v0
	s_nop 0
	v_cndmask_b32_e32 v75, v169, v75, vcc
	v_cmp_le_i32_e32 vcc, v2, v128
	v_add_u32_e32 v2, 57, v0
	s_nop 0
	v_cndmask_b32_e32 v76, v169, v76, vcc
	v_cmp_le_i32_e32 vcc, v2, v128
	v_add_u32_e32 v2, 58, v0
	v_add_u32_e32 v0, 59, v0
	v_cndmask_b32_e32 v77, v169, v77, vcc
	v_cmp_le_i32_e32 vcc, v2, v128
	s_nop 1
	v_cndmask_b32_e32 v78, v169, v78, vcc
	v_cmp_gt_i32_e32 vcc, v0, v128
	s_and_saveexec_b64 s[0:1], vcc
	v_mov_b32_e32 v79, 0xf149f2ca
	s_or_b64 exec, exec, s[0:1]
